# gdn unit prologue: beta/decay logits requested first (they feed the longest dependent chain), single counted wait
# speedup vs baseline: 1.0061x; 1.0056x over previous
; __device__ __forceinline__ void gdn_unit(const Ctx& X, LAS unsigned char* hl, int b, int c, int h, int tid_h, int w4, int lane, int layer) {
;     ...
;         const float* cw = X.in[8] + (size_t)layer * 4 * 768 + h * 64 + cseg * 8;
; #pragma unroll
;         for (int tn = 0; tn < 3; ++tn)
; #pragma unroll
;             for (int k = 0; k < 4; ++k) { const f32x4* wp = (const f32x4*)(cw + k * 768 + tn * 256); wq[tn][k][0] = wp[0]; wq[tn][k][1] = wp[1]; }
;         u32x4 rawv[7];
; #pragma unroll
;         for (int n = 0; n < 7; ++n) { const int item = tid_h + 256 * n; const int seg = item & 7; int rowid = item >> 3; rowid = rowid < 201 ? rowid : 200;
;             const int tn = rowid / 67, rr = rowid - tn * 67; const int tt = c * 64 - 3 + rr; const int ttc = tt < 0 ? 0 : tt;
;             const u32x4 v = *(const u32x4*)(proj + ((size_t)b * T + ttc) * LDP + C_GQ + tn * 256 + h * 64 + seg * 8);
;             rawv[n] = tt < 0 ? (u32x4){0u, 0u, 0u, 0u} : v; }
;         float g = 0.f, bt = 0.f;
;         if (tid_h < 64) {
;             const bf16_t* pr = proj + ((size_t)b * T + c * 64 + tid_h) * LDP;
;             const float* gba = WSP(const float, WS_GBA) + ((size_t)b * T + c * 64 + tid_h) * 8; const float gb = gba[h], ga = gba[4 + h];
.LBB0_318:
	s_and_b64 vcc, exec, s[0:1]
	s_cbranch_vccz .LBB0_356
	v_cmp_gt_i32_e32 vcc, 64, v132
	s_and_saveexec_b64 s[94:95], vcc
	s_cbranch_execz .Lgba_early_done
	s_lshl_b32 s98, s21, 6
	s_lshl_b32 s99, s24, 13
	s_or_b32 s98, s98, s99
	s_mov_b32 s99, s17
	v_mov_b32_e32 v240, v132
	v_ashrrev_i32_e32 v241, 31, v132
	v_readlane_b32 s100, v252, 31
	v_readlane_b32 s101, v252, 32
	v_lshl_add_u64 v[240:241], v[240:241], 0, s[98:99]
	v_lshlrev_b64 v[240:241], 5, v[240:241]
	s_lshl_b32 s98, s23, 2
	v_lshl_add_u64 v[240:241], s[100:101], 0, v[240:241]
	v_lshl_add_u64 v[240:241], v[240:241], 0, s[98:99]
	s_add_i32 s98, s23, s14
	s_lshl_b64 s[98:99], s[98:99], 2
	v_readlane_b32 s100, v253, 40
	v_readlane_b32 s101, v253, 41
	v_readlane_b32 s82, v253, 42
	v_readlane_b32 s83, v253, 43
	s_add_u32 s100, s100, s98
	s_addc_u32 s101, s101, s99
	s_add_u32 s82, s82, s98
	s_addc_u32 s83, s83, s99
	global_load_dword v242, v[240:241], off
	global_load_dword v243, v[240:241], off offset:16
	global_load_dword v244, v157, s[100:101]
	global_load_dword v245, v157, s[82:83]
.Lgba_early_done:
	s_or_b64 exec, exec, s[94:95]
	v_readlane_b32 s0, v252, 59
	s_lshl_b32 s16, s23, 6
	v_lshlrev_b32_e32 v134, 3, v132
	v_mov_b32_e32 v186, s0
	v_readlane_b32 s0, v252, 60
	v_mov_b32_e32 v182, s36
	v_and_b32_e32 v190, 56, v134
	v_mov_b32_e32 v187, s0
	v_readlane_b32 s0, v252, 61
	v_lshlrev_b32_e32 v156, 2, v190
	v_add_u32_e32 v189, 0x2400, v182
	v_mov_b32_e32 v185, s0
	v_readlane_b32 s0, v252, 63
	s_mov_b64 s[4:5], 0x1800
	v_add_u32_e32 v183, 0x2400, v189
	v_mov_b32_e32 v135, s0
	s_lshl_b64 s[0:1], s[16:17], 2
	s_add_u32 s0, s9, s0
	s_addc_u32 s1, s15, s1
	v_lshl_add_u64 v[6:7], s[0:1], 0, v[156:157]
	v_lshl_add_u64 v[8:9], v[6:7], 0, s[4:5]
	v_add_u32_e32 v181, 0x2400, v183
	s_movk_i32 s4, 0x1000
	v_add_co_u32_e32 v10, vcc, s4, v6
	v_add_u32_e32 v131, 0x2400, v181
	s_mov_b64 s[4:5], 0x2400
	v_addc_co_u32_e32 v11, vcc, 0, v7, vcc
	v_add_u32_e32 v184, 0x2400, v131
	v_lshl_add_u64 v[12:13], v[6:7], 0, s[4:5]
	s_movk_i32 s4, 0x2000
	v_add_co_u32_e32 v18, vcc, s4, v6
	v_add_u32_e32 v188, 0x100, v185
	v_lshl_add_u64 v[14:15], v[6:7], 0, s[42:43]
	s_mov_b64 s[4:5], 0x1c00
	global_load_dwordx4 v[58:61], v156, s[0:1] offset:16
	global_load_dwordx4 v[66:69], v156, s[0:1]
	global_load_dwordx4 v[98:101], v156, s[0:1] offset:3088
	global_load_dwordx4 v[74:77], v156, s[0:1] offset:3072
	v_addc_co_u32_e32 v19, vcc, 0, v7, vcc
	global_load_dwordx4 v[38:41], v156, s[0:1] offset:1040
	global_load_dwordx4 v[46:49], v156, s[0:1] offset:1024
	global_load_dwordx4 v[94:97], v[12:13], off offset:16
	global_load_dwordx4 v[50:53], v[18:19], off offset:-4096
	v_lshl_add_u64 v[12:13], v[6:7], 0, s[4:5]
	global_load_dwordx4 v[62:65], v[10:11], off offset:2048
	global_load_dwordx4 v[34:37], v[10:11], off offset:3072
	global_load_dwordx4 v[90:93], v[14:15], off offset:16
	global_load_dwordx4 v[30:33], v[12:13], off offset:16
	s_nop 0
	global_load_dwordx4 v[14:17], v156, s[0:1] offset:2064
	global_load_dwordx4 v[22:25], v156, s[0:1] offset:2048
	s_mov_b64 s[0:1], 0x1400
	s_mov_b64 s[4:5], 0x2800
	v_lshl_add_u64 v[20:21], v[6:7], 0, s[0:1]
	s_mov_b64 s[0:1], 0x2000
	v_lshl_add_u64 v[12:13], v[6:7], 0, s[4:5]
	global_load_dwordx4 v[54:57], v[8:9], off offset:16
	global_load_dwordx4 v[26:29], v[10:11], off offset:1024
	global_load_dwordx4 v[86:89], v[12:13], off offset:16
	global_load_dwordx4 v[82:85], v[20:21], off offset:16
	v_lshl_add_u64 v[8:9], v[6:7], 0, s[0:1]
	s_mov_b64 s[0:1], 0x2c00
	v_lshl_add_u64 v[78:79], v[6:7], 0, s[0:1]
	global_load_dwordx4 v[70:73], v[18:19], off offset:1024
	global_load_dwordx4 v[10:13], v[18:19], off
	global_load_dwordx4 v[42:45], v[18:19], off offset:2048
	s_nop 0
	global_load_dwordx4 v[18:21], v[18:19], off offset:3072
	s_nop 0
	global_load_dwordx4 v[6:9], v[8:9], off offset:16
	s_nop 0
	global_load_dwordx4 v[78:81], v[78:79], off offset:16
	v_ashrrev_i32_e32 v191, 3, v132
	v_min_i32_e32 v102, 0xc8, v191
	s_mov_b32 s0, 0x7a44c6b
	v_mul_hi_i32 v103, v102, s0
	v_lshrrev_b32_e32 v104, 31, v103
	v_ashrrev_i32_e32 v103, 1, v103
	s_lshl_b32 s4, s21, 6
	v_add_u32_e32 v103, v103, v104
	s_movk_i32 s0, 0xffbd
	s_add_i32 s6, s4, -3
	v_mul_lo_u32 v104, v103, s0
	v_add3_u32 v104, v102, s6, v104
	s_lshl_b32 s5, s24, 13
	v_cmp_lt_i32_e32 vcc, -1, v104
	v_mov_b32_e32 v102, 0
	v_lshlrev_b32_e32 v156, 1, v190
	v_mov_b32_e32 v106, 0
	v_mov_b32_e32 v107, 0
	v_mov_b32_e32 v108, 0
	v_mov_b32_e32 v109, 0
	s_and_saveexec_b64 s[0:1], vcc
	s_cbranch_execz .LBB0_321
	v_add_u32_e32 v106, s5, v104
	v_mov_b64_e32 v[104:105], s[30:31]
	v_mad_u64_u32 v[104:105], s[24:25], v106, s71, v[104:105]
	v_lshlrev_b32_e32 v106, 8, v103
	v_ashrrev_i32_e32 v107, 31, v106
	v_lshl_add_u64 v[104:105], v[106:107], 1, v[104:105]
	s_lshl_b32 s24, s16, 1
	s_mov_b32 s25, s17
	v_lshl_add_u64 v[104:105], v[104:105], 0, s[24:25]
	v_lshl_add_u64 v[104:105], v[104:105], 0, v[156:157]
	v_add_co_u32_e32 v104, vcc, 0xb500000, v104
	s_nop 1
	v_addc_co_u32_e32 v105, vcc, 0, v105, vcc
	global_load_dwordx4 v[106:109], v[104:105], off offset:3072

; __device__ __forceinline__ float fexp(float x) { return __expf(x); }
; __device__ __forceinline__ float sigmoid_f(float x) { return frcp(1.0f + fexp(-x)); }
; __device__ __forceinline__ float softplus_f(float x) { return fmaxf(x, 0.f) + log1pf(expf(-fabsf(x))); }
; __device__ __forceinline__ void gdn_unit(const Ctx& X, LAS unsigned char* hl, int b, int c, int h, int tid_h, int w4, int lane, int layer) {
;     ...
;         float g = 0.f, bt = 0.f;
;         if (tid_h < 64) {
;             const bf16_t* pr = proj + ((size_t)b * T + c * 64 + tid_h) * LDP;
;             const float* gba = WSP(const float, WS_GBA) + ((size_t)b * T + c * 64 + tid_h) * 8; const float gb = gba[h], ga = gba[4 + h];
;             g = -fexp(X.in[9][layer * 4 + h]) * softplus_f(ga + X.in[10][layer * 4 + h]);
; #pragma unroll
;             for (int o = 1; o < 64; o <<= 1) { const float t = __shfl_up(g, o); if (lane >= o) g += t; }
;             bt = sigmoid_f(gb);
.LBB0_333:
	s_or_b64 exec, exec, s[0:1]
	v_cmp_gt_i32_e32 vcc, 64, v132
	s_and_saveexec_b64 s[0:1], vcc
	s_cbranch_execz .LBB0_335
	s_or_b32 s16, s4, s5
	v_ashrrev_i32_e32 v133, 31, v132
	v_lshl_add_u64 v[142:143], v[132:133], 0, s[16:17]
	v_readlane_b32 s4, v252, 31
	v_lshlrev_b64 v[142:143], 5, v[142:143]
	v_readlane_b32 s5, v252, 32
	s_lshl_b32 s16, s23, 2
	v_readlane_b32 s44, v253, 38
	v_lshl_add_u64 v[142:143], s[4:5], 0, v[142:143]
	v_lshl_add_u64 v[142:143], v[142:143], 0, s[16:17]
	s_add_i32 s16, s23, s14
	s_lshl_b64 s[4:5], s[16:17], 2
	v_readlane_b32 s46, v253, 40
	v_readlane_b32 s47, v253, 41
	s_add_u32 s6, s46, s4
	v_readlane_b32 s48, v253, 42
	s_addc_u32 s7, s47, s5
	v_readlane_b32 s49, v253, 43
	s_add_u32 s4, s48, s4
	s_addc_u32 s5, s49, s5
	s_waitcnt vmcnt(31)
	v_mov_b32_e32 v133, v242
	v_mov_b32_e32 v142, v243
	v_mov_b32_e32 v167, 0x7f800000
	v_mov_b32_e32 v143, v244
	v_mov_b32_e32 v144, v245
	s_mov_b32 s4, 0xbfb8aa3b
	s_movk_i32 s44, 0x90
	s_mov_b32 s66, 0xbfb8aa3b
	v_readlane_b32 s45, v253, 39
	v_readlane_b32 s50, v253, 44
	v_readlane_b32 s51, v253, 45
	v_readlane_b32 s52, v253, 46
	v_readlane_b32 s53, v253, 47
	v_readlane_b32 s54, v253, 48
	v_readlane_b32 s55, v253, 49
	v_readlane_b32 s56, v253, 50
	v_readlane_b32 s57, v253, 51
	v_readlane_b32 s58, v253, 52
	v_readlane_b32 s59, v253, 53
	s_nop 0
	v_mul_f32_e32 v133, 0xbfb8aa3b, v133
	v_exp_f32_e32 v133, v133
	s_nop 0
	v_mul_f32_e32 v143, 0x3fb8aa3b, v143
	s_nop 0
	v_add_f32_e32 v142, v142, v144
	v_mul_f32_e64 v144, |v142|, s4
	v_fma_f32 v145, |v142|, s4, -v144
	s_mov_b32 s4, 0xb2a5705f
	v_rndne_f32_e32 v146, v144
	v_fma_f32 v145, |v142|, s4, v145
	v_sub_f32_e32 v144, v144, v146
	v_add_f32_e32 v144, v144, v145
	v_exp_f32_e32 v144, v144
	v_cvt_i32_f32_e32 v145, v146
	s_mov_b32 s4, 0x42ce8ed0
	v_cmp_ngt_f32_e64 vcc, |v142|, s4
	s_mov_b32 s4, 0xc2b17218
	v_ldexp_f32 v144, v144, v145
	v_cndmask_b32_e32 v144, 0, v144, vcc
	v_cmp_nlt_f32_e64 vcc, |v142|, s4
	v_max_f32_e32 v166, 0, v142
	s_mov_b32 s4, 0x3f2aaaab
	v_cndmask_b32_e32 v142, v167, v144, vcc
	v_add_f32_e32 v146, 1.0, v142
	v_add_f32_e32 v144, -1.0, v146
	v_sub_f32_e32 v145, v144, v146
	v_add_f32_e32 v145, 1.0, v145
	v_sub_f32_e32 v144, v142, v144
	v_add_f32_e32 v147, v144, v145
	v_frexp_mant_f32_e32 v144, v146
	v_cmp_gt_f32_e32 vcc, s4, v144
	v_cvt_f64_f32_e32 v[144:145], v146
	v_frexp_exp_i32_f64_e32 v144, v[144:145]
	v_subbrev_co_u32_e32 v152, vcc, 0, v144, vcc
	v_sub_u32_e32 v144, 0, v152
	v_ldexp_f32 v145, v146, v144
	v_add_f32_e32 v146, -1.0, v145
	v_add_f32_e32 v148, 1.0, v145
	v_ldexp_f32 v144, v147, v144
	v_add_f32_e32 v147, 1.0, v146
	v_add_f32_e32 v149, -1.0, v148
	v_sub_f32_e32 v147, v145, v147
	v_sub_f32_e32 v145, v145, v149
	v_add_f32_e32 v147, v144, v147
	v_add_f32_e32 v144, v144, v145
	v_add_f32_e32 v153, v148, v144
	v_rcp_f32_e32 v162, v153
	v_sub_f32_e32 v145, v148, v153
	v_add_f32_e32 v155, v144, v145
	v_add_f32_e32 v145, v146, v147
	v_mul_f32_e32 v164, v145, v162
	v_sub_f32_e32 v144, v146, v145
	v_mul_f32_e32 v146, v153, v164
	v_fma_f32 v148, v164, v153, -v146
	v_fmac_f32_e32 v148, v164, v155
	v_add_f32_e32 v163, v147, v144
	v_add_f32_e32 v144, v146, v148
	v_sub_f32_e32 v147, v145, v144
	v_pk_add_f32 v[150:151], v[144:145], v[146:147] neg_lo:[0,1] neg_hi:[0,1]
	v_mov_b32_e32 v149, v144
	v_pk_add_f32 v[144:145], v[150:151], v[148:149] neg_lo:[0,1] neg_hi:[0,1]
	s_mov_b32 s4, 0x3f317218
	v_add_f32_e32 v145, v163, v145
	v_add_f32_e32 v144, v144, v145
	v_add_f32_e32 v145, v147, v144
	v_mul_f32_e32 v163, v162, v145
	v_mul_f32_e32 v146, v153, v163
	v_fma_f32 v148, v163, v153, -v146
	v_fmac_f32_e32 v148, v163, v155
	v_sub_f32_e32 v147, v147, v145
	v_add_f32_e32 v153, v144, v147
	v_add_f32_e32 v144, v146, v148
	v_sub_f32_e32 v147, v145, v144
	v_pk_add_f32 v[150:151], v[144:145], v[146:147] neg_lo:[0,1] neg_hi:[0,1]
	v_mov_b32_e32 v149, v144
	v_pk_add_f32 v[144:145], v[150:151], v[148:149] neg_lo:[0,1] neg_hi:[0,1]
	v_exp_f32_e32 v143, v143
	v_add_f32_e32 v145, v153, v145
	v_add_f32_e32 v144, v144, v145
	v_add_f32_e32 v145, v164, v163
	v_add_f32_e32 v144, v147, v144
	v_sub_f32_e32 v146, v145, v164
	v_mul_f32_e32 v144, v162, v144
	v_sub_f32_e32 v146, v163, v146
	v_add_f32_e32 v146, v146, v144
	v_add_f32_e32 v148, v145, v146
	v_mul_f32_e32 v149, v148, v148
	v_fmamk_f32 v144, v149, 0x3e9b6dac, v235
	v_fmaak_f32 v155, v149, v144, 0x3f2aaada
	v_cvt_f32_i32_e32 v144, v152
	v_sub_f32_e32 v145, v148, v145
	v_sub_f32_e32 v145, v146, v145
	v_ldexp_f32 v150, v145, 1
	v_mul_f32_e32 v145, v148, v149
	v_ldexp_f32 v147, v148, 1
	v_pk_mul_f32 v[148:149], v[144:145], v[154:155]
	v_add_f32_e32 v133, 1.0, v133
	v_fma_f32 v146, v144, s4, -v148
	v_fmac_f32_e32 v146, 0xb102e308, v144
	v_pk_add_f32 v[144:145], v[148:149], v[146:147]
	s_mov_b32 s4, 0x7f800000
	v_sub_f32_e32 v147, v145, v147
	v_sub_f32_e32 v147, v149, v147
	v_add_f32_e32 v151, v150, v147
	v_mov_b32_e32 v150, v148
	v_pk_add_f32 v[148:149], v[144:145], v[148:149] neg_lo:[0,1] neg_hi:[0,1]
	v_pk_add_f32 v[152:153], v[144:145], v[150:151]
	v_mov_b32_e32 v147, v144
	v_mov_b32_e32 v149, v153
	v_pk_add_f32 v[162:163], v[146:147], v[148:149] neg_lo:[0,1] neg_hi:[0,1]
	v_pk_add_f32 v[146:147], v[146:147], v[148:149]
	v_mov_b32_e32 v150, v151
	v_pk_add_f32 v[148:149], v[146:147], v[144:145] op_sel:[1,0] op_sel_hi:[0,1] neg_lo:[0,1] neg_hi:[0,1]
	v_pk_add_f32 v[164:165], v[152:153], v[148:149] op_sel_hi:[1,0] neg_lo:[0,1] neg_hi:[0,1]
	v_mov_b32_e32 v152, v153
	v_mov_b32_e32 v153, v147
	v_pk_mov_b32 v[148:149], v[144:145], v[148:149] op_sel:[1,0]
	v_mov_b32_e32 v151, v144
	v_pk_add_f32 v[148:149], v[152:153], v[148:149] neg_lo:[0,1] neg_hi:[0,1]
	v_mov_b32_e32 v164, v162
	v_pk_add_f32 v[144:145], v[150:151], v[148:149] neg_lo:[0,1] neg_hi:[0,1]
	v_mov_b32_e32 v163, v147
	v_pk_add_f32 v[148:149], v[164:165], v[144:145]
	v_cmp_neq_f32_e32 vcc, s4, v142
	v_pk_add_f32 v[150:151], v[148:149], v[148:149] op_sel:[0,1] op_sel_hi:[1,0]
	s_mov_b32 s4, 0x33800000
	v_pk_add_f32 v[146:147], v[146:147], v[150:151] op_sel:[1,0] op_sel_hi:[0,1]
	v_mov_b32_e32 v149, v146
	v_pk_add_f32 v[152:153], v[148:149], v[162:163] neg_lo:[0,1] neg_hi:[0,1]
	v_mov_b32_e32 v145, v150
	v_sub_f32_e32 v147, v148, v152
	v_pk_add_f32 v[144:145], v[144:145], v[152:153] neg_lo:[0,1] neg_hi:[0,1]
	v_sub_f32_e32 v147, v162, v147
	v_add_f32_e32 v144, v144, v147
	v_add_f32_e32 v144, v144, v145
	v_add_f32_e32 v144, v146, v144
	v_cndmask_b32_e32 v144, v167, v144, vcc
	v_cmp_lt_f32_e64 vcc, |v142|, s4
	v_add_u32_e32 v146, -1, v230
	v_rcp_f32_e32 v133, v133
	v_cndmask_b32_e32 v142, v144, v142, vcc
	v_add_f32_e32 v144, v166, v142
	v_and_b32_e32 v142, 64, v230
	v_cmp_lt_i32_e32 vcc, v146, v142
	v_mul_f32_e64 v145, v144, -v143
	s_nop 0
	v_cndmask_b32_e32 v146, v146, v230, vcc
	v_lshlrev_b32_e32 v146, 2, v146
	ds_bpermute_b32 v146, v146, v145
	v_cmp_gt_i32_e32 vcc, 1, v130
	s_waitcnt lgkmcnt(0)
; __device__ __forceinline__ float sigmoid_f(float x) { return frcp(1.0f + fexp(-x)); }
; __device__ __forceinline__ void gdn_unit(const Ctx& X, LAS unsigned char* hl, int b, int c, int h, int tid_h, int w4, int lane, int layer) {
;     ...
;             for (int o = 1; o < 64; o <<= 1) { const float t = __shfl_up(g, o); if (lane >= o) g += t; }
;             bt = sigmoid_f(gb);
;             Gs[tid_h] = g; Bs[tid_h] = bt;
	v_fma_f32 v143, v144, -v143, v146
	v_add_u32_e32 v144, -2, v230
	v_cndmask_b32_e32 v143, v143, v145, vcc
	v_cmp_lt_i32_e32 vcc, v144, v142
	s_nop 1
	v_cndmask_b32_e32 v144, v144, v230, vcc
	v_lshlrev_b32_e32 v144, 2, v144
	ds_bpermute_b32 v144, v144, v143
	v_cmp_gt_i32_e32 vcc, 2, v130
	s_waitcnt lgkmcnt(0)
	v_add_f32_e32 v144, v143, v144
	v_cndmask_b32_e32 v143, v144, v143, vcc
	v_add_u32_e32 v144, -4, v230
	v_cmp_lt_i32_e32 vcc, v144, v142
	s_nop 1
	v_cndmask_b32_e32 v144, v144, v230, vcc
	v_lshlrev_b32_e32 v144, 2, v144
	ds_bpermute_b32 v144, v144, v143
	v_cmp_gt_i32_e32 vcc, 4, v130
	s_waitcnt lgkmcnt(0)
	v_add_f32_e32 v144, v143, v144
	v_cndmask_b32_e32 v143, v144, v143, vcc
	v_add_u32_e32 v144, -8, v230
	v_cmp_lt_i32_e32 vcc, v144, v142
	s_nop 1
	v_cndmask_b32_e32 v144, v144, v230, vcc
	v_lshlrev_b32_e32 v144, 2, v144
	ds_bpermute_b32 v144, v144, v143
	v_cmp_gt_i32_e32 vcc, 8, v130
	s_waitcnt lgkmcnt(0)
	v_add_f32_e32 v144, v143, v144
	v_cndmask_b32_e32 v143, v144, v143, vcc
	v_add_u32_e32 v144, -16, v230
	v_cmp_lt_i32_e32 vcc, v144, v142
	s_nop 1
	v_cndmask_b32_e32 v144, v144, v230, vcc
	v_lshlrev_b32_e32 v144, 2, v144
	ds_bpermute_b32 v144, v144, v143
	v_cmp_gt_i32_e32 vcc, 16, v130
	s_waitcnt lgkmcnt(0)
	v_add_f32_e32 v144, v143, v144
	v_cndmask_b32_e32 v143, v144, v143, vcc
	v_subrev_u32_e32 v144, 32, v230
	v_cmp_lt_i32_e32 vcc, v144, v142
	s_nop 1
	v_cndmask_b32_e32 v142, v144, v230, vcc
	v_lshlrev_b32_e32 v142, 2, v142
	ds_bpermute_b32 v142, v142, v143
	v_cmp_gt_i32_e32 vcc, 32, v130
	s_waitcnt lgkmcnt(0)
	v_add_f32_e32 v142, v143, v142
	v_cndmask_b32_e32 v142, v142, v143, vcc
	v_lshlrev_b32_e32 v143, 2, v132
	v_add_u32_e32 v144, v185, v143
	ds_write_b32 v144, v142
	v_add_u32_e32 v142, v188, v143
	ds_write_b32 v142, v133

; __device__ __forceinline__ float bf2f(bf16_t b) { return __uint_as_float((unsigned)b << 16); }
; __device__ __forceinline__ bf16_t f2bf(float f) { return (bf16_t)(pk2(f, 0.f) & 0xffffu); }
; __device__ __forceinline__ float fexp(float x) { return __expf(x); }
; __device__ __forceinline__ void gdn_unit(const Ctx& X, LAS unsigned char* hl, int b, int c, int h, int tid_h, int w4, int lane, int layer) {
;     ...
;     {
;         f32x4 acc[4];
;         const float eG63 = fexp(Gs[63]);
; #pragma unroll
;         for (int ct = 0; ct < 4; ++ct) acc[ct] = mma16(P, 16 * w4, WT, 16 * ct, (f32x4){0.f, 0.f, 0.f, 0.f}, r, q);
;         bf16_t* qe = WSP(bf16_t, WS_QEFF) + (size_t)uid * 4096;
; #pragma unroll
;         for (int ct = 0; ct < 4; ++ct)
; #pragma unroll
;             for (int j = 0; j < 4; ++j) { const int ii = 16 * w4 + 4 * q + j, col = 16 * ct + r;
;                 qe[ii * 64 + col] = f2bf(bf2f(Q[ii * LT + col]) * fexp(Gs[ii]) - acc[ct][j]); }
; #pragma unroll
;         for (int ct = 0; ct < 4; ++ct) acc[ct] = mma16(P, 16 * w4, UT, 16 * ct, (f32x4){0.f, 0.f, 0.f, 0.f}, r, q);
;         store_oloc(WSP(bf16_t, WS_OLOC), uid, w4, lane, acc);
; #pragma unroll
;         for (int ct = 0; ct < 4; ++ct) acc[ct] = mma16(KDT, 16 * w4, WT, 16 * ct, (f32x4){0.f, 0.f, 0.f, 0.f}, r, q);
;         bf16_t* mm = WSP(bf16_t, WS_MM) + (size_t)(uid - 2048) * 4096;
; #pragma unroll
;         for (int ct = 0; ct < 4; ++ct)
; #pragma unroll
;             for (int j = 0; j < 4; ++j) { const int ii = 16 * w4 + 4 * q + j, col = 16 * ct + r;
;                 mm[((w4 * 2 + (ct >> 1)) * 64 + (r >> 2) * 16 + 4 * q + j) * 8 + (ct & 1) * 4 + (r & 3)] = f2bf((ii == col ? eG63 : 0.f) - acc[ct][j]); }
; #pragma unroll
;         for (int ct = 0; ct < 4; ++ct) acc[ct] = mma16(KDT, 16 * w4, UT, 16 * ct, (f32x4){0.f, 0.f, 0.f, 0.f}, r, q);
;         store_bc(WSP(bf16_t, WS_BCS), uid, w4, r, q, acc);
;     }
.LBB0_619:
	s_waitcnt lgkmcnt(0)
	s_barrier
	v_bfe_u32 v54, v224, 6, 2
	v_and_b32_e32 v55, 15, v232
	v_lshrrev_b32_e32 v56, 4, v232
	v_lshl_or_b32 v57, v54, 4, v55
	v_mul_u32_u24_e32 v58, 0x90, v57
	v_mul_u32_u24_e32 v59, 0x90, v55
	v_lshl_add_u32 v60, v56, 4, v58
	v_lshl_add_u32 v61, v56, 4, v59
	v_add_u32_e32 v60, v182, v60
	v_add_u32_e32 v61, v182, v61
	v_add_u32_e32 v178, 0xb400, v60
	v_add_u32_e32 v179, 0x4800, v61
	v_add_u32_e32 v60, 0x9000, v60
	v_add_u32_e32 v61, 0x6c00, v61
	ds_read_b128 v[6:9], v178
	ds_read_b128 v[10:13], v178 offset:64
	ds_read_b128 v[22:25], v179
	ds_read_b128 v[26:29], v179 offset:64
	ds_read_b128 v[30:33], v179 offset:2304
	ds_read_b128 v[34:37], v179 offset:2368
	ds_read_b128 v[38:41], v179 offset:4608
	ds_read_b128 v[42:45], v179 offset:4672
	ds_read_b128 v[46:49], v179 offset:6912
	ds_read_b128 v[50:53], v179 offset:6976
	ds_read_b128 v[14:17], v60
	ds_read_b128 v[18:21], v60 offset:64
	v_lshl_add_u32 v62, v57, 2, v185
	v_lshl_add_u32 v63, v56, 3, v58
	v_add_u32_e32 v63, v182, v63
	ds_read_b32 v176, v62
	ds_read_b32 v177, v185 offset:252
	s_lshl_b32 s0, s22, 9
	s_lshl_b32 s1, s23, 7
	s_add_i32 s1, s1, s0
	s_or_b32 s0, s1, s21
	s_ashr_i32 s1, s0, 31
	s_lshl_b64 s[0:1], s[0:1], 13
	s_add_u32 s4, s89, s0
	s_addc_u32 s5, s78, s1
	s_add_u32 s6, s79, s0
	s_addc_u32 s7, s80, s1
	v_readlane_b32 s98, v253, 3
	v_readlane_b32 s99, v253, 4
	s_add_u32 s98, s98, s0
	s_addc_u32 s99, s99, s1
	s_add_u32 s98, s98, 0xff000000
	s_addc_u32 s99, s99, -1
	s_add_u32 s100, s74, s0
	s_addc_u32 s101, s75, s1
	v_readfirstlane_b32 s32, v54
	v_lshlrev_b32_e32 v64, 11, v54
	v_lshlrev_b32_e32 v65, 5, v232
	v_lshl_add_u32 v64, v232, 4, v64
	v_lshlrev_b32_e32 v66, 9, v54
	v_lshl_add_u32 v66, v232, 3, v66
	v_add_u32_e32 v67, 0x1000, v66
	v_lshlrev_b32_e32 v71, 7, v57
	v_lshl_add_u32 v71, v56, 3, v71
	v_lshlrev_b32_e32 v70, 2, v56
	v_sub_u32_e32 v70, v55, v70
	s_waitcnt lgkmcnt(4)
	v_mfma_f32_16x16x32_bf16 v[134:137], v[22:25], v[6:9], 0
	v_mfma_f32_16x16x32_bf16 v[138:141], v[30:33], v[6:9], 0
	v_mfma_f32_16x16x32_bf16 v[142:145], v[38:41], v[6:9], 0
	v_mfma_f32_16x16x32_bf16 v[146:149], v[46:49], v[6:9], 0
	v_mfma_f32_16x16x32_bf16 v[134:137], v[26:29], v[10:13], v[134:137]
	v_mfma_f32_16x16x32_bf16 v[138:141], v[34:37], v[10:13], v[138:141]
	v_mfma_f32_16x16x32_bf16 v[142:145], v[42:45], v[10:13], v[142:145]
	v_mfma_f32_16x16x32_bf16 v[146:149], v[50:53], v[10:13], v[146:149]
	ds_read_b64 v[150:151], v63
	ds_read_b64 v[152:153], v63 offset:32
	ds_read_b64 v[172:173], v63 offset:64
	ds_read_b64 v[174:175], v63 offset:96
	ds_read_b128 v[186:189], v61
	ds_read_b128 v[190:193], v61 offset:64
	ds_read_b128 v[194:197], v61 offset:2304
	ds_read_b128 v[198:201], v61 offset:2368
	ds_read_b128 v[202:205], v61 offset:4608
	ds_read_b128 v[206:209], v61 offset:4672
	ds_read_b128 v[210:213], v61 offset:6912
	s_waitcnt lgkmcnt(13)
	v_mfma_f32_16x16x32_bf16 v[236:239], v[22:25], v[14:17], 0
	v_mfma_f32_16x16x32_bf16 v[240:243], v[30:33], v[14:17], 0
	v_mfma_f32_16x16x32_bf16 v[244:247], v[38:41], v[14:17], 0
	v_mfma_f32_16x16x32_bf16 v[248:251], v[46:49], v[14:17], 0
	v_mfma_f32_16x16x32_bf16 v[236:239], v[26:29], v[18:21], v[236:239]
	v_mfma_f32_16x16x32_bf16 v[240:243], v[34:37], v[18:21], v[240:243]
	v_mfma_f32_16x16x32_bf16 v[244:247], v[42:45], v[18:21], v[244:247]
	v_mfma_f32_16x16x32_bf16 v[248:251], v[50:53], v[18:21], v[248:251]
	ds_read_b128 v[214:217], v61 offset:6976
	s_waitcnt lgkmcnt(8)
	v_mul_f32_e32 v176, 0x3fb8aa3b, v176
	v_mul_f32_e32 v177, 0x3fb8aa3b, v177
	v_exp_f32_e32 v176, v176
	v_exp_f32_e32 v177, v177
	v_cmp_eq_u32_e32 vcc, 0, v70
	v_cmp_eq_u32_e64 s[0:1], 1, v70
	v_lshlrev_b32_e32 v76, 16, v150
	v_and_b32_e32 v77, 0xffff0000, v150
	v_cndmask_b32_e32 v72, 0, v177, vcc
	v_cndmask_b32_e64 v73, 0, v177, s[0:1]
	v_cmp_eq_u32_e32 vcc, 2, v70
	v_cmp_eq_u32_e64 s[0:1], 3, v70
	v_lshlrev_b32_e32 v78, 16, v151
	v_and_b32_e32 v79, 0xffff0000, v151
	v_cndmask_b32_e32 v74, 0, v177, vcc
	v_cndmask_b32_e64 v75, 0, v177, s[0:1]
	s_waitcnt lgkmcnt(0)
	v_mfma_f32_16x16x32_bf16 v[84:87], v[6:9], v[186:189], 0
	v_mfma_f32_16x16x32_bf16 v[88:91], v[6:9], v[194:197], 0
	v_mfma_f32_16x16x32_bf16 v[92:95], v[6:9], v[202:205], 0
	v_mfma_f32_16x16x32_bf16 v[96:99], v[6:9], v[210:213], 0
	v_mfma_f32_16x16x32_bf16 v[114:117], v[14:17], v[186:189], 0
	v_mfma_f32_16x16x32_bf16 v[118:121], v[14:17], v[194:197], 0
	v_mfma_f32_16x16x32_bf16 v[122:125], v[14:17], v[202:205], 0
	v_mfma_f32_16x16x32_bf16 v[126:129], v[14:17], v[210:213], 0
	v_mfma_f32_16x16x32_bf16 v[84:87], v[10:13], v[190:193], v[84:87]
	v_mfma_f32_16x16x32_bf16 v[88:91], v[10:13], v[198:201], v[88:91]
	v_mfma_f32_16x16x32_bf16 v[92:95], v[10:13], v[206:209], v[92:95]
	v_mfma_f32_16x16x32_bf16 v[96:99], v[10:13], v[214:217], v[96:99]
	v_mfma_f32_16x16x32_bf16 v[114:117], v[18:21], v[190:193], v[114:117]
	v_mfma_f32_16x16x32_bf16 v[118:121], v[18:21], v[198:201], v[118:121]
	v_mfma_f32_16x16x32_bf16 v[122:125], v[18:21], v[206:209], v[122:125]
	v_mfma_f32_16x16x32_bf16 v[126:129], v[18:21], v[214:217], v[126:129]
	v_fma_f32 v76, v176, v76, -v134
	v_fma_f32 v77, v176, v77, -v135
	v_fma_f32 v78, v176, v78, -v136
	v_fma_f32 v79, v176, v79, -v137
	v_cvt_pk_bf16_f32 v218, v76, v77
	v_cvt_pk_bf16_f32 v219, v78, v79
	global_store_dwordx2 v71, v[218:219], s[4:5]
	v_lshlrev_b32_e32 v76, 16, v152
	v_and_b32_e32 v77, 0xffff0000, v152
	v_lshlrev_b32_e32 v78, 16, v153
	v_and_b32_e32 v79, 0xffff0000, v153
	v_fma_f32 v76, v176, v76, -v138
	v_fma_f32 v77, v176, v77, -v139
	v_fma_f32 v78, v176, v78, -v140
	v_fma_f32 v79, v176, v79, -v141
	v_cvt_pk_bf16_f32 v220, v76, v77
; __device__ __forceinline__ bf16_t f2bf(float f) { return (bf16_t)(pk2(f, 0.f) & 0xffffu); }
; #define LBAR() do { asm volatile("s_waitcnt lgkmcnt(0)" ::: "memory"); __builtin_amdgcn_s_barrier(); asm volatile("" ::: "memory"); } while (0)
; __device__ __forceinline__ void gdn_unit(const Ctx& X, LAS unsigned char* hl, int b, int c, int h, int tid_h, int w4, int lane, int layer) {
;     ...
;         bf16_t* mm = WSP(bf16_t, WS_MM) + (size_t)(uid - 2048) * 4096;
; #pragma unroll
;         for (int ct = 0; ct < 4; ++ct)
; #pragma unroll
;             for (int j = 0; j < 4; ++j) { const int ii = 16 * w4 + 4 * q + j, col = 16 * ct + r;
;                 mm[((w4 * 2 + (ct >> 1)) * 64 + (r >> 2) * 16 + 4 * q + j) * 8 + (ct & 1) * 4 + (r & 3)] = f2bf((ii == col ? eG63 : 0.f) - acc[ct][j]); }
; #pragma unroll
;         for (int ct = 0; ct < 4; ++ct) acc[ct] = mma16(KDT, 16 * w4, UT, 16 * ct, (f32x4){0.f, 0.f, 0.f, 0.f}, r, q);
;         store_bc(WSP(bf16_t, WS_BCS), uid, w4, r, q, acc);
;     }
;     LBAR();
	v_cvt_pk_bf16_f32 v221, v78, v79
	global_store_dwordx2 v71, v[220:221], s[4:5] offset:32
	v_lshlrev_b32_e32 v76, 16, v172
	v_and_b32_e32 v77, 0xffff0000, v172
	v_lshlrev_b32_e32 v78, 16, v173
	v_and_b32_e32 v79, 0xffff0000, v173
	v_fma_f32 v76, v176, v76, -v142
	v_fma_f32 v77, v176, v77, -v143
	v_fma_f32 v78, v176, v78, -v144
	v_fma_f32 v79, v176, v79, -v145
	v_cvt_pk_bf16_f32 v222, v76, v77
	v_cvt_pk_bf16_f32 v223, v78, v79
	global_store_dwordx2 v71, v[222:223], s[4:5] offset:64
	v_lshlrev_b32_e32 v76, 16, v174
	v_and_b32_e32 v77, 0xffff0000, v174
	v_lshlrev_b32_e32 v78, 16, v175
	v_and_b32_e32 v79, 0xffff0000, v175
	v_fma_f32 v76, v176, v76, -v146
	v_fma_f32 v77, v176, v77, -v147
	v_fma_f32 v78, v176, v78, -v148
	v_fma_f32 v79, v176, v79, -v149
	v_cvt_pk_bf16_f32 v226, v76, v77
	v_cvt_pk_bf16_f32 v227, v78, v79
	global_store_dwordx2 v71, v[226:227], s[4:5] offset:96
	s_cmp_eq_u32 s32, 0
	s_cselect_b32 s0, 1.0, 0
	v_fma_f32 v76, v72, s0, -v236
	v_fma_f32 v77, v73, s0, -v237
	v_fma_f32 v78, v74, s0, -v238
	v_fma_f32 v79, v75, s0, -v239
	v_cvt_pk_bf16_f32 v100, v76, v77
	v_cvt_pk_bf16_f32 v101, v78, v79
	s_cmp_eq_u32 s32, 1
	s_cselect_b32 s0, 1.0, 0
	v_fma_f32 v76, v72, s0, -v240
	v_fma_f32 v77, v73, s0, -v241
	v_fma_f32 v78, v74, s0, -v242
	v_fma_f32 v79, v75, s0, -v243
	v_cvt_pk_bf16_f32 v102, v76, v77
	v_cvt_pk_bf16_f32 v103, v78, v79
	global_store_dwordx4 v64, v[100:103], s[98:99]
	s_cmp_eq_u32 s32, 2
	s_cselect_b32 s0, 1.0, 0
	v_fma_f32 v76, v72, s0, -v244
	v_fma_f32 v77, v73, s0, -v245
	v_fma_f32 v78, v74, s0, -v246
	v_fma_f32 v79, v75, s0, -v247
	v_cvt_pk_bf16_f32 v104, v76, v77
	v_cvt_pk_bf16_f32 v105, v78, v79
	s_cmp_eq_u32 s32, 3
	s_cselect_b32 s0, 1.0, 0
	v_fma_f32 v76, v72, s0, -v248
	v_fma_f32 v77, v73, s0, -v249
	v_fma_f32 v78, v74, s0, -v250
	v_fma_f32 v79, v75, s0, -v251
	v_cvt_pk_bf16_f32 v106, v76, v77
	v_cvt_pk_bf16_f32 v107, v78, v79
	global_store_dwordx4 v64, v[104:107], s[98:99] offset:1024
	v_cvt_pk_bf16_f32 v108, v84, v85
	v_cvt_pk_bf16_f32 v109, v86, v87
	v_cvt_pk_bf16_f32 v110, v88, v89
	v_cvt_pk_bf16_f32 v111, v90, v91
	global_store_dwordx4 v65, v[108:111], s[6:7] nt
	v_cvt_pk_bf16_f32 v80, v92, v93
	v_cvt_pk_bf16_f32 v81, v94, v95
	v_cvt_pk_bf16_f32 v82, v96, v97
	v_cvt_pk_bf16_f32 v83, v98, v99
	global_store_dwordx4 v65, v[80:83], s[6:7] offset:16 nt
	v_cvt_pk_bf16_f32 v40, v114, v115
	v_cvt_pk_bf16_f32 v41, v116, v117
	global_store_dwordx2 v66, v[40:41], s[100:101]
	v_cvt_pk_bf16_f32 v42, v118, v119
	v_cvt_pk_bf16_f32 v43, v120, v121
	global_store_dwordx2 v66, v[42:43], s[100:101] offset:2048
	v_cvt_pk_bf16_f32 v44, v122, v123
	v_cvt_pk_bf16_f32 v45, v124, v125
	global_store_dwordx2 v67, v[44:45], s[100:101]
	v_cvt_pk_bf16_f32 v46, v126, v127
	v_cvt_pk_bf16_f32 v47, v128, v129
	global_store_dwordx2 v67, v[46:47], s[100:101] offset:2048
	s_branch .Lgdn_p4_pad_end
	s_nop 0
	s_nop 0
	s_nop 0
	s_nop 0
	s_nop 0
	s_nop 0
	s_nop 0
	s_nop 0
	s_nop 0
	s_nop 0
	s_nop 0
	s_nop 0
	s_nop 0
	s_nop 0
	s_nop 0
	s_nop 0
	s_nop 0
	s_nop 0
	s_nop 0
	s_nop 0
	s_nop 0
	s_nop 0
	s_nop 0
	s_nop 0
	s_nop 0
	s_nop 0
	s_nop 0
	s_nop 0
	s_nop 0
	s_nop 0
	s_nop 0
	s_nop 0
	s_nop 0
	s_nop 0
	s_nop 0
	s_nop 0
	s_nop 0
	s_nop 0
	s_nop 0
	s_nop 0
	s_nop 0
	s_nop 0
	s_nop 0
	s_nop 0
	s_nop 0
	s_nop 0
	s_nop 0
	s_nop 0
	s_nop 0
	s_nop 0
	s_nop 0
	s_nop 0
	s_nop 0
	s_nop 0
	s_nop 0
	s_nop 0
	s_nop 0
	s_nop 0
	s_nop 0
	s_nop 0
	s_nop 0
	s_nop 0
	s_nop 0
	s_nop 0
	s_nop 0
	s_nop 0
	s_nop 0
	s_nop 0
	s_nop 0
	s_nop 0
	s_nop 0
	s_nop 0
	s_nop 0
	s_nop 0
	s_nop 0
	s_nop 0
	s_nop 0
	s_nop 0
	s_nop 0
	s_nop 0
	s_nop 0
	s_nop 0
	s_nop 0
	s_nop 0
	s_nop 0
	s_nop 0
	s_nop 0
	s_nop 0
	s_nop 0
	s_nop 0
	s_nop 0
	s_nop 0
	s_nop 0
	s_nop 0
	s_nop 0
	s_nop 0
	s_nop 0
	s_nop 0
	s_nop 0
	s_nop 0
	s_nop 0
	s_nop 0
	s_nop 0
	s_nop 0
	s_nop 0
	s_nop 0
	s_nop 0
	s_nop 0
	s_nop 0
	s_nop 0
	s_nop 0
	s_nop 0
	s_nop 0
	s_nop 0
	s_nop 0
	s_nop 0
	s_nop 0
	s_nop 0
	s_nop 0
	s_nop 0
	s_nop 0
	s_nop 0
	s_nop 0
	s_nop 0
	s_nop 0
	s_nop 0
	s_nop 0
	s_nop 0
	s_nop 0
	s_nop 0
	s_nop 0
	s_nop 0
	s_nop 0
	s_nop 0
	s_nop 0
	s_nop 0
	s_nop 0
	s_nop 0
	s_nop 0
	s_nop 0
	s_nop 0
	s_nop 0
	s_nop 0
	s_nop 0
	s_nop 0
	s_nop 0
	s_nop 0
	s_nop 0
	s_nop 0
	s_nop 0
	s_nop 0
	s_nop 0
	s_nop 0
	s_nop 0
	s_nop 0
	s_nop 0
	s_nop 0
	s_nop 0
	s_nop 0
	s_nop 0
	s_nop 0
	s_nop 0
	s_nop 0
	s_nop 0
	s_nop 0
	s_nop 0
	s_nop 0
	s_nop 0
	s_nop 0
	s_nop 0
	s_nop 0
	s_nop 0
	s_nop 0
	s_nop 0
	s_nop 0
	s_nop 0
	s_nop 0
	s_nop 0
	s_nop 0
	s_nop 0
	s_nop 0
	s_nop 0
	s_nop 0
	s_nop 0
	s_nop 0
	s_nop 0
	s_nop 0
	s_nop 0
	s_nop 0
	s_nop 0
	s_nop 0
	s_nop 0
	s_nop 0
	s_nop 0
	s_nop 0
	s_nop 0
	s_nop 0
	s_nop 0
	s_nop 0
	s_nop 0
	s_nop 0
	s_nop 0
	s_nop 0
	s_nop 0
	s_nop 0
	s_nop 0
	s_nop 0
	s_nop 0
	s_nop 0
	s_nop 0
	s_nop 0
	s_nop 0
	s_nop 0
	s_nop 0
	s_nop 0
	s_nop 0
	s_nop 0
	s_nop 0
	s_nop 0
	s_nop 0
	s_nop 0
	s_nop 0
	s_nop 0
	s_nop 0
	s_nop 0
	s_nop 0
	s_nop 0
	s_nop 0
	s_nop 0
	s_nop 0
	s_nop 0
	s_nop 0
	s_nop 0
	s_nop 0
	s_nop 0
	s_nop 0
	s_nop 0
	s_nop 0
	s_nop 0
	s_nop 0
	s_nop 0
	s_nop 0
	s_nop 0
	s_nop 0
	s_nop 0
	s_nop 0
	s_nop 0
	s_nop 0
	s_nop 0
	s_nop 0
	s_nop 0
	s_nop 0
	s_nop 0
	s_nop 0
	s_nop 0
	s_nop 0
	s_nop 0
	s_nop 0
	s_nop 0
	s_nop 0
	s_nop 0
	s_nop 0
	s_nop 0
	s_nop 0
	s_nop 0
	s_nop 0
	s_nop 0
	s_nop 0
	s_nop 0
	s_nop 0
	s_nop 0
	s_nop 0
	s_nop 0
	s_nop 0
	s_nop 0
	s_nop 0
	s_nop 0
	s_nop 0
	s_nop 0
	s_nop 0
	s_nop 0
	s_nop 0
	s_nop 0
	s_nop 0
	s_nop 0
	s_nop 0
	s_nop 0
	s_nop 0
	s_nop 0
	s_nop 0
	s_nop 0
	s_nop 0
	s_nop 0
	s_nop 0
	s_nop 0
	s_nop 0
.Lgdn_p4_pad_end:
	s_waitcnt lgkmcnt(0)
	s_barrier
	s_mov_b64 s[0:1], 0
